# v14: DA online-softmax row-max exchange between lane halves by v_permlane32_swap instead of an LDS ds_bpermute round trip in the K/V tile loop
# speedup vs baseline: 1.0633x; 1.0038x over previous
; DI void da_item(const Params& P, int layer, int b, int h, int qt, char* mb, char* smem) {
;     ...
;         mx = fmaxf(mx, __shfl_xor(mx, 32));
;         const float mn = fmaxf(m, mx);
;         const float corr = __builtin_amdgcn_exp2f(m - mn);
;         m = mn;
;         float ls = 0.f;
; #pragma unroll
;         for (int kb = 0; kb < 2; kb++)
; #pragma unroll
;           for (int i = 0; i < 16; i++) { const float p = __builtin_amdgcn_exp2f(s[kb][i] - mn); s[kb][i] = p; ls += p; }
;         l = l * corr + ls;
;         if (__ballot(corr != 1.f) != 0ull) {
; #pragma unroll
;           for (int dt = 0; dt < 4; dt++)
; #pragma unroll
;             for (int i = 0; i < 16; i++) o[dt][i] *= corr;
;         }
.LBB0_4125:
	s_or_b64 exec, exec, s[30:31]
	v_mov_b32_e32 v82, v3
	s_nop 1
	v_permlane32_swap_b32_e32 v82, v3
	s_nop 1
	v_max3_f32 v3, v226, v3, v82
	v_sub_f32_e32 v82, v226, v3
	v_exp_f32_e32 v82, v82
	s_nop 0
	v_cmp_neq_f32_e32 vcc, 1.0, v82
	s_cbranch_vccz .LBB0_4127
	v_pk_mul_f32 v[80:81], v[80:81], v[82:83] op_sel_hi:[1,0]
	v_pk_mul_f32 v[78:79], v[78:79], v[82:83] op_sel_hi:[1,0]
	v_pk_mul_f32 v[76:77], v[76:77], v[82:83] op_sel_hi:[1,0]
	v_pk_mul_f32 v[74:75], v[74:75], v[82:83] op_sel_hi:[1,0]
	v_pk_mul_f32 v[72:73], v[72:73], v[82:83] op_sel_hi:[1,0]
	v_pk_mul_f32 v[70:71], v[70:71], v[82:83] op_sel_hi:[1,0]
	v_pk_mul_f32 v[68:69], v[68:69], v[82:83] op_sel_hi:[1,0]
	v_pk_mul_f32 v[66:67], v[66:67], v[82:83] op_sel_hi:[1,0]
	v_pk_mul_f32 v[64:65], v[64:65], v[82:83] op_sel_hi:[1,0]
	v_pk_mul_f32 v[62:63], v[62:63], v[82:83] op_sel_hi:[1,0]
	v_pk_mul_f32 v[60:61], v[60:61], v[82:83] op_sel_hi:[1,0]
	v_pk_mul_f32 v[58:59], v[58:59], v[82:83] op_sel_hi:[1,0]
	v_pk_mul_f32 v[56:57], v[56:57], v[82:83] op_sel_hi:[1,0]
	v_pk_mul_f32 v[54:55], v[54:55], v[82:83] op_sel_hi:[1,0]
	v_pk_mul_f32 v[52:53], v[52:53], v[82:83] op_sel_hi:[1,0]
	v_pk_mul_f32 v[50:51], v[50:51], v[82:83] op_sel_hi:[1,0]
	v_pk_mul_f32 v[48:49], v[48:49], v[82:83] op_sel_hi:[1,0]
	v_pk_mul_f32 v[46:47], v[46:47], v[82:83] op_sel_hi:[1,0]
	v_pk_mul_f32 v[44:45], v[44:45], v[82:83] op_sel_hi:[1,0]
	v_pk_mul_f32 v[42:43], v[42:43], v[82:83] op_sel_hi:[1,0]
	v_pk_mul_f32 v[40:41], v[40:41], v[82:83] op_sel_hi:[1,0]
	v_pk_mul_f32 v[38:39], v[38:39], v[82:83] op_sel_hi:[1,0]
	v_pk_mul_f32 v[36:37], v[36:37], v[82:83] op_sel_hi:[1,0]
	v_pk_mul_f32 v[34:35], v[34:35], v[82:83] op_sel_hi:[1,0]
	v_pk_mul_f32 v[32:33], v[32:33], v[82:83] op_sel_hi:[1,0]
	v_pk_mul_f32 v[30:31], v[30:31], v[82:83] op_sel_hi:[1,0]
	v_pk_mul_f32 v[28:29], v[28:29], v[82:83] op_sel_hi:[1,0]
	v_pk_mul_f32 v[26:27], v[26:27], v[82:83] op_sel_hi:[1,0]
	v_pk_mul_f32 v[24:25], v[24:25], v[82:83] op_sel_hi:[1,0]
	v_pk_mul_f32 v[22:23], v[22:23], v[82:83] op_sel_hi:[1,0]
	v_pk_mul_f32 v[20:21], v[20:21], v[82:83] op_sel_hi:[1,0]
	v_pk_mul_f32 v[18:19], v[18:19], v[82:83] op_sel_hi:[1,0]

; DI void da_item(const Params& P, int layer, int b, int h, int qt, char* mb, char* smem) {
;     ...
;         mx = fmaxf(mx, __shfl_xor(mx, 32));
;         const float mn = fmaxf(m, mx);
;         const float corr = __builtin_amdgcn_exp2f(m - mn);
;         m = mn;
;         float ls = 0.f;
; #pragma unroll
;         for (int kb = 0; kb < 2; kb++)
; #pragma unroll
;           for (int i = 0; i < 16; i++) { const float p = __builtin_amdgcn_exp2f(s[kb][i] - mn); s[kb][i] = p; ls += p; }
;         l = l * corr + ls;
;         if (__ballot(corr != 1.f) != 0ull) {
; #pragma unroll
;           for (int dt = 0; dt < 4; dt++)
; #pragma unroll
;             for (int i = 0; i < 16; i++) o[dt][i] *= corr;
;         }
.LBB0_8084:
	s_or_b64 exec, exec, s[30:31]
	v_mov_b32_e32 v82, v3
	s_nop 1
	v_permlane32_swap_b32_e32 v82, v3
	s_nop 1
	v_max3_f32 v3, v227, v3, v82
	v_sub_f32_e32 v82, v227, v3
	v_exp_f32_e32 v82, v82
	s_nop 0
	v_cmp_neq_f32_e32 vcc, 1.0, v82
	s_cbranch_vccz .LBB0_8086
	v_pk_mul_f32 v[80:81], v[80:81], v[82:83] op_sel_hi:[1,0]
	v_pk_mul_f32 v[78:79], v[78:79], v[82:83] op_sel_hi:[1,0]
	v_pk_mul_f32 v[76:77], v[76:77], v[82:83] op_sel_hi:[1,0]
	v_pk_mul_f32 v[74:75], v[74:75], v[82:83] op_sel_hi:[1,0]
	v_pk_mul_f32 v[72:73], v[72:73], v[82:83] op_sel_hi:[1,0]
	v_pk_mul_f32 v[70:71], v[70:71], v[82:83] op_sel_hi:[1,0]
	v_pk_mul_f32 v[68:69], v[68:69], v[82:83] op_sel_hi:[1,0]
	v_pk_mul_f32 v[66:67], v[66:67], v[82:83] op_sel_hi:[1,0]
	v_pk_mul_f32 v[64:65], v[64:65], v[82:83] op_sel_hi:[1,0]
	v_pk_mul_f32 v[62:63], v[62:63], v[82:83] op_sel_hi:[1,0]
	v_pk_mul_f32 v[60:61], v[60:61], v[82:83] op_sel_hi:[1,0]
	v_pk_mul_f32 v[58:59], v[58:59], v[82:83] op_sel_hi:[1,0]
	v_pk_mul_f32 v[56:57], v[56:57], v[82:83] op_sel_hi:[1,0]
	v_pk_mul_f32 v[54:55], v[54:55], v[82:83] op_sel_hi:[1,0]
	v_pk_mul_f32 v[52:53], v[52:53], v[82:83] op_sel_hi:[1,0]
	v_pk_mul_f32 v[50:51], v[50:51], v[82:83] op_sel_hi:[1,0]
	v_pk_mul_f32 v[48:49], v[48:49], v[82:83] op_sel_hi:[1,0]
	v_pk_mul_f32 v[46:47], v[46:47], v[82:83] op_sel_hi:[1,0]
	v_pk_mul_f32 v[44:45], v[44:45], v[82:83] op_sel_hi:[1,0]
	v_pk_mul_f32 v[42:43], v[42:43], v[82:83] op_sel_hi:[1,0]
	v_pk_mul_f32 v[40:41], v[40:41], v[82:83] op_sel_hi:[1,0]
	v_pk_mul_f32 v[38:39], v[38:39], v[82:83] op_sel_hi:[1,0]
	v_pk_mul_f32 v[36:37], v[36:37], v[82:83] op_sel_hi:[1,0]
	v_pk_mul_f32 v[34:35], v[34:35], v[82:83] op_sel_hi:[1,0]
	v_pk_mul_f32 v[32:33], v[32:33], v[82:83] op_sel_hi:[1,0]
	v_pk_mul_f32 v[30:31], v[30:31], v[82:83] op_sel_hi:[1,0]
	v_pk_mul_f32 v[28:29], v[28:29], v[82:83] op_sel_hi:[1,0]
	v_pk_mul_f32 v[26:27], v[26:27], v[82:83] op_sel_hi:[1,0]
	v_pk_mul_f32 v[24:25], v[24:25], v[82:83] op_sel_hi:[1,0]
	v_pk_mul_f32 v[22:23], v[22:23], v[82:83] op_sel_hi:[1,0]
	v_pk_mul_f32 v[20:21], v[20:21], v[82:83] op_sel_hi:[1,0]
	v_pk_mul_f32 v[18:19], v[18:19], v[82:83] op_sel_hi:[1,0]
